# filter MLP (phase 0): all 97 weight loads of an item issued up front instead of 11 serialized load batches
# speedup vs baseline: 1.0045x; 1.0045x over previous
.LBB0_118:
	s_or_b64 exec, exec, s[10:11]
	v_lshl_or_b32 v12, v3, 6, v16
	v_ashrrev_i32_e32 v13, 31, v12
	v_lshl_add_u64 v[14:15], v[12:13], 2, s[26:27]
	global_load_dword v28, v[14:15], off
	v_mul_i32_i24_e32 v14, 0x840, v3
	v_ashrrev_i32_e32 v15, 31, v14
	v_lshl_add_u64 v[14:15], v[14:15], 2, v[8:9]
	s_mov_b32 s10, 0
	global_load_dword v51, v[14:15], off offset:-2560
	global_load_dword v52, v[14:15], off offset:-2304
	global_load_dword v53, v[14:15], off offset:-2048
	global_load_dword v54, v[14:15], off offset:-1792
	global_load_dword v55, v[14:15], off offset:-1536
	global_load_dword v56, v[14:15], off offset:-1280
	global_load_dword v57, v[14:15], off offset:-1024
	global_load_dword v58, v[14:15], off offset:-768
	global_load_dword v59, v[14:15], off offset:-512
	global_load_dword v60, v[14:15], off offset:-256
	global_load_dword v61, v[14:15], off offset:0
	v_lshl_add_u64 v[14:15], v[14:15], 0, s[16:17]
	global_load_dword v62, v[14:15], off offset:-2560
	global_load_dword v63, v[14:15], off offset:-2304
	global_load_dword v64, v[14:15], off offset:-2048
	global_load_dword v65, v[14:15], off offset:-1792
	global_load_dword v66, v[14:15], off offset:-1536
	global_load_dword v67, v[14:15], off offset:-1280
	global_load_dword v68, v[14:15], off offset:-1024
	global_load_dword v69, v[14:15], off offset:-768
	global_load_dword v70, v[14:15], off offset:-512
	global_load_dword v71, v[14:15], off offset:-256
	global_load_dword v72, v[14:15], off offset:0
	v_lshl_add_u64 v[14:15], v[14:15], 0, s[16:17]
	global_load_dword v73, v[14:15], off offset:-2560
	global_load_dword v74, v[14:15], off offset:-2304
	global_load_dword v75, v[14:15], off offset:-2048
	global_load_dword v76, v[14:15], off offset:-1792
	global_load_dword v77, v[14:15], off offset:-1536
	global_load_dword v78, v[14:15], off offset:-1280
	global_load_dword v79, v[14:15], off offset:-1024
	global_load_dword v80, v[14:15], off offset:-768
	global_load_dword v81, v[14:15], off offset:-512
	global_load_dword v82, v[14:15], off offset:-256
	global_load_dword v83, v[14:15], off offset:0
	v_lshl_add_u64 v[14:15], v[14:15], 0, s[16:17]
	v_lshlrev_b32_e32 v120, 12, v3
	v_ashrrev_i32_e32 v121, 31, v120
	v_lshl_add_u64 v[120:121], v[120:121], 2, v[10:11]
	global_load_dword v155, v[120:121], off offset:-1792
	global_load_dword v156, v[120:121], off offset:-1536
	global_load_dword v157, v[120:121], off offset:-1280
	global_load_dword v158, v[120:121], off offset:-1024
	global_load_dword v159, v[120:121], off offset:-768
	global_load_dword v160, v[120:121], off offset:-512
	global_load_dword v161, v[120:121], off offset:-256
	global_load_dword v162, v[120:121], off offset:0
	v_lshl_add_u64 v[120:121], v[120:121], 0, s[18:19]
	global_load_dword v163, v[120:121], off offset:-1792
	global_load_dword v164, v[120:121], off offset:-1536
	global_load_dword v165, v[120:121], off offset:-1280
	global_load_dword v166, v[120:121], off offset:-1024
	global_load_dword v167, v[120:121], off offset:-768
	global_load_dword v168, v[120:121], off offset:-512
	global_load_dword v169, v[120:121], off offset:-256
	global_load_dword v170, v[120:121], off offset:0
	v_lshl_add_u64 v[120:121], v[120:121], 0, s[18:19]
	global_load_dword v171, v[120:121], off offset:-1792
	global_load_dword v172, v[120:121], off offset:-1536
	global_load_dword v173, v[120:121], off offset:-1280
	global_load_dword v174, v[120:121], off offset:-1024
	global_load_dword v175, v[120:121], off offset:-768
	global_load_dword v176, v[120:121], off offset:-512
	global_load_dword v177, v[120:121], off offset:-256
	global_load_dword v178, v[120:121], off offset:0
	v_lshl_add_u64 v[120:121], v[120:121], 0, s[18:19]
	global_load_dword v179, v[120:121], off offset:-1792
	global_load_dword v180, v[120:121], off offset:-1536
	global_load_dword v181, v[120:121], off offset:-1280
	global_load_dword v182, v[120:121], off offset:-1024
	global_load_dword v183, v[120:121], off offset:-768
	global_load_dword v184, v[120:121], off offset:-512
	global_load_dword v185, v[120:121], off offset:-256
	global_load_dword v186, v[120:121], off offset:0
	v_lshl_add_u64 v[120:121], v[120:121], 0, s[18:19]
	global_load_dword v187, v[120:121], off offset:-1792
	global_load_dword v188, v[120:121], off offset:-1536
	global_load_dword v189, v[120:121], off offset:-1280
	global_load_dword v190, v[120:121], off offset:-1024
	global_load_dword v191, v[120:121], off offset:-768
	global_load_dword v192, v[120:121], off offset:-512
	global_load_dword v193, v[120:121], off offset:-256
	global_load_dword v194, v[120:121], off offset:0
	v_lshl_add_u64 v[120:121], v[120:121], 0, s[18:19]
	global_load_dword v195, v[120:121], off offset:-1792
	global_load_dword v196, v[120:121], off offset:-1536
	global_load_dword v197, v[120:121], off offset:-1280
	global_load_dword v198, v[120:121], off offset:-1024
	global_load_dword v199, v[120:121], off offset:-768
	global_load_dword v200, v[120:121], off offset:-512
	global_load_dword v201, v[120:121], off offset:-256
	global_load_dword v202, v[120:121], off offset:0
	v_lshl_add_u64 v[120:121], v[120:121], 0, s[18:19]
	global_load_dword v203, v[120:121], off offset:-1792
	global_load_dword v204, v[120:121], off offset:-1536
	global_load_dword v205, v[120:121], off offset:-1280
	global_load_dword v206, v[120:121], off offset:-1024
	global_load_dword v207, v[120:121], off offset:-768
	global_load_dword v208, v[120:121], off offset:-512
	global_load_dword v209, v[120:121], off offset:-256
	global_load_dword v210, v[120:121], off offset:0
	v_lshl_add_u64 v[120:121], v[120:121], 0, s[18:19]
	global_load_dword v211, v[120:121], off offset:-1792
	global_load_dword v212, v[120:121], off offset:-1536
	global_load_dword v213, v[120:121], off offset:-1280
	global_load_dword v214, v[120:121], off offset:-1024
	global_load_dword v215, v[120:121], off offset:-768
	global_load_dword v216, v[120:121], off offset:-512
	global_load_dword v217, v[120:121], off offset:-256
	global_load_dword v218, v[120:121], off offset:0
	v_lshl_add_u64 v[120:121], v[120:121], 0, s[18:19]
	v_add_u32_e32 v122, 0, v18
	ds_bpermute_b32 v84, v122, v4
	ds_bpermute_b32 v85, v122, v4 offset:4
	ds_bpermute_b32 v86, v122, v4 offset:8
	ds_bpermute_b32 v87, v122, v4 offset:12
	ds_bpermute_b32 v88, v122, v4 offset:16
	ds_bpermute_b32 v89, v122, v4 offset:20
	ds_bpermute_b32 v90, v122, v4 offset:24
	ds_bpermute_b32 v91, v122, v4 offset:28
	ds_bpermute_b32 v92, v122, v4 offset:32
	ds_bpermute_b32 v93, v122, v4 offset:36
	ds_bpermute_b32 v94, v122, v4 offset:40
	v_add_u32_e32 v122, 44, v18
	ds_bpermute_b32 v95, v122, v4
	ds_bpermute_b32 v96, v122, v4 offset:4
	ds_bpermute_b32 v97, v122, v4 offset:8
	ds_bpermute_b32 v98, v122, v4 offset:12
	ds_bpermute_b32 v99, v122, v4 offset:16
	ds_bpermute_b32 v100, v122, v4 offset:20
	ds_bpermute_b32 v101, v122, v4 offset:24
	ds_bpermute_b32 v102, v122, v4 offset:28
	ds_bpermute_b32 v103, v122, v4 offset:32
	ds_bpermute_b32 v104, v122, v4 offset:36
	ds_bpermute_b32 v105, v122, v4 offset:40
	v_add_u32_e32 v122, 88, v18
	ds_bpermute_b32 v106, v122, v4
	ds_bpermute_b32 v107, v122, v4 offset:4
	ds_bpermute_b32 v108, v122, v4 offset:8
	ds_bpermute_b32 v109, v122, v4 offset:12
	ds_bpermute_b32 v110, v122, v4 offset:16
	ds_bpermute_b32 v111, v122, v4 offset:20
	ds_bpermute_b32 v112, v122, v4 offset:24
	ds_bpermute_b32 v113, v122, v4 offset:28
	ds_bpermute_b32 v114, v122, v4 offset:32
	ds_bpermute_b32 v115, v122, v4 offset:36
	ds_bpermute_b32 v116, v122, v4 offset:40
	s_waitcnt vmcnt(63) lgkmcnt(0)
	v_fmac_f32_e32 v28, v51, v84
	v_fmac_f32_e32 v28, v52, v85
	v_fmac_f32_e32 v28, v53, v86
	v_fmac_f32_e32 v28, v54, v87
	v_fmac_f32_e32 v28, v55, v88
	v_fmac_f32_e32 v28, v56, v89
	v_fmac_f32_e32 v28, v57, v90
	v_fmac_f32_e32 v28, v58, v91
	v_fmac_f32_e32 v28, v59, v92
	v_fmac_f32_e32 v28, v60, v93
	v_fmac_f32_e32 v28, v61, v94
	v_fmac_f32_e32 v28, v62, v95
	v_fmac_f32_e32 v28, v63, v96
	v_fmac_f32_e32 v28, v64, v97
	v_fmac_f32_e32 v28, v65, v98
	v_fmac_f32_e32 v28, v66, v99
	v_fmac_f32_e32 v28, v67, v100
	v_fmac_f32_e32 v28, v68, v101
	v_fmac_f32_e32 v28, v69, v102
	v_fmac_f32_e32 v28, v70, v103
	v_fmac_f32_e32 v28, v71, v104
	v_fmac_f32_e32 v28, v72, v105
	v_fmac_f32_e32 v28, v73, v106
	v_fmac_f32_e32 v28, v74, v107
	v_fmac_f32_e32 v28, v75, v108
	v_fmac_f32_e32 v28, v76, v109
	v_fmac_f32_e32 v28, v77, v110
	v_fmac_f32_e32 v28, v78, v111
	v_fmac_f32_e32 v28, v79, v112
	v_fmac_f32_e32 v28, v80, v113
	v_fmac_f32_e32 v28, v81, v114
	v_fmac_f32_e32 v28, v82, v115
	v_fmac_f32_e32 v28, v83, v116
	v_and_b32_e32 v15, 0x7fffffff, v28
	v_cmp_nlt_f32_e64 s[10:11], |v28|, s41
	s_and_saveexec_b64 s[12:13], s[10:11]
	s_xor_b64 s[20:21], exec, s[12:13]
	s_cbranch_execz .LBB0_122
	v_lshrrev_b32_e32 v4, 23, v15
	v_add_u32_e32 v4, 0xffffff88, v4
	v_cmp_lt_u32_e32 vcc, 63, v4
	s_nop 1
	v_cndmask_b32_e32 v14, 0, v24, vcc
	v_add_u32_e32 v4, v14, v4
	v_cmp_lt_u32_e64 s[10:11], 31, v4
	s_nop 1
	v_cndmask_b32_e64 v14, 0, v25, s[10:11]
	v_add_u32_e32 v4, v14, v4
	v_cmp_lt_u32_e64 s[12:13], 31, v4
	s_nop 1
	v_cndmask_b32_e64 v14, 0, v25, s[12:13]
	v_add_u32_e32 v14, v14, v4
	v_and_b32_e32 v4, 0x7fffff, v15
	v_or_b32_e32 v29, 0x800000, v4
	v_mad_u64_u32 v[30:31], s[14:15], v29, s42, 0
	v_mov_b32_e32 v4, v31
	v_mad_u64_u32 v[32:33], s[14:15], v29, s43, v[4:5]
	v_mov_b32_e32 v4, v33
	v_mad_u64_u32 v[34:35], s[14:15], v29, s44, v[4:5]
	v_mov_b32_e32 v4, v35
	v_mad_u64_u32 v[36:37], s[14:15], v29, s45, v[4:5]
	v_mov_b32_e32 v4, v37
	v_mad_u64_u32 v[38:39], s[14:15], v29, s46, v[4:5]
	v_mov_b32_e32 v4, v39
	v_mad_u64_u32 v[40:41], s[14:15], v29, s47, v[4:5]
	v_mov_b32_e32 v4, v41
	v_mad_u64_u32 v[42:43], s[14:15], v29, s48, v[4:5]
	v_cndmask_b32_e32 v31, v40, v36, vcc
	v_cndmask_b32_e32 v4, v42, v38, vcc
	v_cndmask_b32_e32 v33, v43, v40, vcc
	v_cndmask_b32_e64 v29, v4, v31, s[10:11]
	v_cndmask_b32_e64 v4, v33, v4, s[10:11]
	v_cndmask_b32_e32 v33, v38, v34, vcc
	v_cndmask_b32_e64 v31, v31, v33, s[10:11]
	v_sub_u32_e32 v35, 32, v14
	v_cmp_eq_u32_e64 s[14:15], 0, v14
	v_cndmask_b32_e32 v14, v36, v32, vcc
	v_cndmask_b32_e64 v4, v4, v29, s[12:13]
	v_cndmask_b32_e64 v29, v29, v31, s[12:13]
	v_cndmask_b32_e64 v32, v33, v14, s[10:11]
	v_alignbit_b32 v37, v4, v29, v35
	v_cndmask_b32_e64 v31, v31, v32, s[12:13]
	v_cndmask_b32_e64 v4, v37, v4, s[14:15]
	v_alignbit_b32 v33, v29, v31, v35
	v_cndmask_b32_e32 v30, v34, v30, vcc
	v_cndmask_b32_e64 v29, v33, v29, s[14:15]
	v_bfe_u32 v37, v4, 29, 1
	v_cndmask_b32_e64 v14, v14, v30, s[10:11]
	v_alignbit_b32 v33, v4, v29, 30
	v_sub_u32_e32 v38, 0, v37
	v_cndmask_b32_e64 v14, v32, v14, s[12:13]
	v_xor_b32_e32 v33, v33, v38
	v_alignbit_b32 v30, v31, v14, v35
	v_cndmask_b32_e64 v30, v30, v31, s[14:15]
	v_ffbh_u32_e32 v31, v33
	v_alignbit_b32 v29, v29, v30, 30
	v_min_u32_e32 v31, 32, v31
	v_alignbit_b32 v14, v30, v14, 30
	v_xor_b32_e32 v29, v29, v38
	v_sub_u32_e32 v32, 31, v31
	v_xor_b32_e32 v14, v14, v38
	v_alignbit_b32 v33, v33, v29, v32
	v_alignbit_b32 v14, v29, v14, v32
	v_alignbit_b32 v29, v33, v14, 9
	v_ffbh_u32_e32 v30, v29
	v_min_u32_e32 v30, 32, v30
	v_lshrrev_b32_e32 v36, 29, v4
	v_not_b32_e32 v32, v30
	v_alignbit_b32 v14, v29, v14, v32
	v_lshlrev_b32_e32 v29, 31, v36
	v_or_b32_e32 v32, 0x33000000, v29
	v_add_lshl_u32 v30, v30, v31, 23
	v_lshrrev_b32_e32 v14, 9, v14
	v_sub_u32_e32 v30, v32, v30
	v_or_b32_e32 v29, 0.5, v29
	v_lshlrev_b32_e32 v31, 23, v31
	v_or_b32_e32 v14, v30, v14
	v_lshrrev_b32_e32 v30, 9, v33
	v_sub_u32_e32 v29, v29, v31
	v_or_b32_e32 v29, v30, v29
	v_mul_f32_e32 v30, 0x3fc90fda, v29
	v_fma_f32 v31, v29, s49, -v30
	v_fmac_f32_e32 v31, 0x33a22168, v29
	v_fmac_f32_e32 v31, 0x3fc90fda, v14
	v_lshrrev_b32_e32 v4, 30, v4
	v_add_f32_e32 v29, v30, v31
	v_add_u32_e32 v4, v37, v4
.LBB0_122:
	s_andn2_saveexec_b64 s[10:11], s[20:21]
	v_mul_f32_e64 v4, |v28|, s50
	v_rndne_f32_e32 v14, v4
	v_cvt_i32_f32_e32 v4, v14
	v_fma_f32 v29, v14, s51, |v28|
	v_fmac_f32_e32 v29, 0xb3a22168, v14
	v_fmac_f32_e32 v29, 0xa7c234c4, v14
	s_or_b64 exec, exec, s[10:11]
	v_lshl_add_u64 v[12:13], v[12:13], 2, s[30:31]
	global_load_dword v14, v[12:13], off
	v_lshlrev_b32_e32 v12, 12, v3
	v_mul_f32_e32 v3, v29, v29
	v_fmamk_f32 v30, v3, 0xb94c1982, v21
	v_fmaak_f32 v30, v3, v30, 0xbe2aaa9d
	v_mul_f32_e32 v30, v3, v30
	v_fmac_f32_e32 v29, v29, v30
	v_fmamk_f32 v30, v3, 0x37d75334, v23
	v_fmaak_f32 v30, v3, v30, 0x3d2aabf7
	v_fmaak_f32 v30, v3, v30, 0xbf000004
	v_fma_f32 v3, v3, v30, 1.0
	v_and_b32_e32 v30, 1, v4
	v_lshlrev_b32_e32 v4, 30, v4
	v_cmp_eq_u32_e32 vcc, 0, v30
	v_and_b32_e32 v4, 0x80000000, v4
	v_xor_b32_e32 v15, v15, v28
	v_cndmask_b32_e32 v3, v3, v29, vcc
	v_xor_b32_e32 v4, v15, v4
	v_ashrrev_i32_e32 v13, 31, v12
	v_xor_b32_e32 v3, v4, v3
	v_cmp_class_f32_e64 vcc, v28, s53
	s_mov_b32 s10, 0
	v_lshl_add_u64 v[12:13], v[12:13], 2, v[10:11]
	v_cndmask_b32_e32 v3, v27, v3, vcc
	v_add_u32_e32 v122, 0, v18
	ds_bpermute_b32 v51, v122, v3
	ds_bpermute_b32 v52, v122, v3 offset:4
	ds_bpermute_b32 v53, v122, v3 offset:8
	ds_bpermute_b32 v54, v122, v3 offset:12
	ds_bpermute_b32 v55, v122, v3 offset:16
	ds_bpermute_b32 v56, v122, v3 offset:20
	ds_bpermute_b32 v57, v122, v3 offset:24
	ds_bpermute_b32 v58, v122, v3 offset:28
	v_add_u32_e32 v122, 32, v18
	ds_bpermute_b32 v59, v122, v3
	ds_bpermute_b32 v60, v122, v3 offset:4
	ds_bpermute_b32 v61, v122, v3 offset:8
	ds_bpermute_b32 v62, v122, v3 offset:12
	ds_bpermute_b32 v63, v122, v3 offset:16
	ds_bpermute_b32 v64, v122, v3 offset:20
	ds_bpermute_b32 v65, v122, v3 offset:24
	ds_bpermute_b32 v66, v122, v3 offset:28
	v_add_u32_e32 v122, 64, v18
	ds_bpermute_b32 v67, v122, v3
	ds_bpermute_b32 v68, v122, v3 offset:4
	ds_bpermute_b32 v69, v122, v3 offset:8
	ds_bpermute_b32 v70, v122, v3 offset:12
	ds_bpermute_b32 v71, v122, v3 offset:16
	ds_bpermute_b32 v72, v122, v3 offset:20
	ds_bpermute_b32 v73, v122, v3 offset:24
	ds_bpermute_b32 v74, v122, v3 offset:28
	v_add_u32_e32 v122, 96, v18
	ds_bpermute_b32 v75, v122, v3
	ds_bpermute_b32 v76, v122, v3 offset:4
	ds_bpermute_b32 v77, v122, v3 offset:8
	ds_bpermute_b32 v78, v122, v3 offset:12
	ds_bpermute_b32 v79, v122, v3 offset:16
	ds_bpermute_b32 v80, v122, v3 offset:20
	ds_bpermute_b32 v81, v122, v3 offset:24
	ds_bpermute_b32 v82, v122, v3 offset:28
	v_add_u32_e32 v122, 128, v18
	ds_bpermute_b32 v83, v122, v3
	ds_bpermute_b32 v84, v122, v3 offset:4
	ds_bpermute_b32 v85, v122, v3 offset:8
	ds_bpermute_b32 v86, v122, v3 offset:12
	ds_bpermute_b32 v87, v122, v3 offset:16
	ds_bpermute_b32 v88, v122, v3 offset:20
	ds_bpermute_b32 v89, v122, v3 offset:24
	ds_bpermute_b32 v90, v122, v3 offset:28
	v_add_u32_e32 v122, 160, v18
	ds_bpermute_b32 v91, v122, v3
	ds_bpermute_b32 v92, v122, v3 offset:4
	ds_bpermute_b32 v93, v122, v3 offset:8
	ds_bpermute_b32 v94, v122, v3 offset:12
	ds_bpermute_b32 v95, v122, v3 offset:16
	ds_bpermute_b32 v96, v122, v3 offset:20
	ds_bpermute_b32 v97, v122, v3 offset:24
	ds_bpermute_b32 v98, v122, v3 offset:28
	v_add_u32_e32 v122, 192, v18
	ds_bpermute_b32 v99, v122, v3
	ds_bpermute_b32 v100, v122, v3 offset:4
	ds_bpermute_b32 v101, v122, v3 offset:8
	ds_bpermute_b32 v102, v122, v3 offset:12
	ds_bpermute_b32 v103, v122, v3 offset:16
	ds_bpermute_b32 v104, v122, v3 offset:20
	ds_bpermute_b32 v105, v122, v3 offset:24
	ds_bpermute_b32 v106, v122, v3 offset:28
	v_add_u32_e32 v122, 224, v18
	ds_bpermute_b32 v107, v122, v3
	ds_bpermute_b32 v108, v122, v3 offset:4
	ds_bpermute_b32 v109, v122, v3 offset:8
	ds_bpermute_b32 v110, v122, v3 offset:12
	ds_bpermute_b32 v111, v122, v3 offset:16
	ds_bpermute_b32 v112, v122, v3 offset:20
	ds_bpermute_b32 v113, v122, v3 offset:24
	ds_bpermute_b32 v114, v122, v3 offset:28
	s_waitcnt vmcnt(0) lgkmcnt(0)
	v_fmac_f32_e32 v14, v155, v51
	v_fmac_f32_e32 v14, v156, v52
	v_fmac_f32_e32 v14, v157, v53
	v_fmac_f32_e32 v14, v158, v54
	v_fmac_f32_e32 v14, v159, v55
	v_fmac_f32_e32 v14, v160, v56
	v_fmac_f32_e32 v14, v161, v57
	v_fmac_f32_e32 v14, v162, v58
	v_fmac_f32_e32 v14, v163, v59
	v_fmac_f32_e32 v14, v164, v60
	v_fmac_f32_e32 v14, v165, v61
	v_fmac_f32_e32 v14, v166, v62
	v_fmac_f32_e32 v14, v167, v63
	v_fmac_f32_e32 v14, v168, v64
	v_fmac_f32_e32 v14, v169, v65
	v_fmac_f32_e32 v14, v170, v66
	v_fmac_f32_e32 v14, v171, v67
	v_fmac_f32_e32 v14, v172, v68
	v_fmac_f32_e32 v14, v173, v69
	v_fmac_f32_e32 v14, v174, v70
	v_fmac_f32_e32 v14, v175, v71
	v_fmac_f32_e32 v14, v176, v72
	v_fmac_f32_e32 v14, v177, v73
	v_fmac_f32_e32 v14, v178, v74
	v_fmac_f32_e32 v14, v179, v75
	v_fmac_f32_e32 v14, v180, v76
	v_fmac_f32_e32 v14, v181, v77
	v_fmac_f32_e32 v14, v182, v78
	v_fmac_f32_e32 v14, v183, v79
	v_fmac_f32_e32 v14, v184, v80
	v_fmac_f32_e32 v14, v185, v81
	v_fmac_f32_e32 v14, v186, v82
	v_fmac_f32_e32 v14, v187, v83
	v_fmac_f32_e32 v14, v188, v84
	v_fmac_f32_e32 v14, v189, v85
	v_fmac_f32_e32 v14, v190, v86
	v_fmac_f32_e32 v14, v191, v87
	v_fmac_f32_e32 v14, v192, v88
	v_fmac_f32_e32 v14, v193, v89
	v_fmac_f32_e32 v14, v194, v90
	v_fmac_f32_e32 v14, v195, v91
	v_fmac_f32_e32 v14, v196, v92
	v_fmac_f32_e32 v14, v197, v93
	v_fmac_f32_e32 v14, v198, v94
	v_fmac_f32_e32 v14, v199, v95
	v_fmac_f32_e32 v14, v200, v96
	v_fmac_f32_e32 v14, v201, v97
	v_fmac_f32_e32 v14, v202, v98
	v_fmac_f32_e32 v14, v203, v99
	v_fmac_f32_e32 v14, v204, v100
	v_fmac_f32_e32 v14, v205, v101
	v_fmac_f32_e32 v14, v206, v102
	v_fmac_f32_e32 v14, v207, v103
	v_fmac_f32_e32 v14, v208, v104
	v_fmac_f32_e32 v14, v209, v105
	v_fmac_f32_e32 v14, v210, v106
	v_fmac_f32_e32 v14, v211, v107
	v_fmac_f32_e32 v14, v212, v108
	v_fmac_f32_e32 v14, v213, v109
	v_fmac_f32_e32 v14, v214, v110
	v_fmac_f32_e32 v14, v215, v111
	v_fmac_f32_e32 v14, v216, v112
	v_fmac_f32_e32 v14, v217, v113
	v_fmac_f32_e32 v14, v218, v114
	v_and_b32_e32 v3, 0x7fffffff, v14
	v_cmp_nlt_f32_e64 s[10:11], |v14|, s41
	s_and_saveexec_b64 s[12:13], s[10:11]
	s_xor_b64 s[20:21], exec, s[12:13]
	s_cbranch_execz .LBB0_128
	v_lshrrev_b32_e32 v4, 23, v3
	v_add_u32_e32 v4, 0xffffff88, v4
	v_cmp_lt_u32_e32 vcc, 63, v4
	s_nop 1
	v_cndmask_b32_e32 v12, 0, v24, vcc
	v_add_u32_e32 v4, v12, v4
	v_cmp_lt_u32_e64 s[10:11], 31, v4
	s_nop 1
	v_cndmask_b32_e64 v12, 0, v25, s[10:11]
	v_add_u32_e32 v4, v12, v4
	v_cmp_lt_u32_e64 s[12:13], 31, v4
	s_nop 1
	v_cndmask_b32_e64 v12, 0, v25, s[12:13]
	v_add_u32_e32 v15, v12, v4
	v_and_b32_e32 v4, 0x7fffff, v3
	v_or_b32_e32 v38, 0x800000, v4
	v_mad_u64_u32 v[12:13], s[14:15], v38, s42, 0
	v_mov_b32_e32 v4, v13
	v_mad_u64_u32 v[28:29], s[14:15], v38, s43, v[4:5]
	v_mov_b32_e32 v4, v29
	v_mad_u64_u32 v[30:31], s[14:15], v38, s44, v[4:5]
	v_mov_b32_e32 v4, v31
	v_mad_u64_u32 v[32:33], s[14:15], v38, s45, v[4:5]
	v_mov_b32_e32 v4, v33
	v_mad_u64_u32 v[34:35], s[14:15], v38, s46, v[4:5]
	v_mov_b32_e32 v4, v35
	v_mad_u64_u32 v[36:37], s[14:15], v38, s47, v[4:5]
	v_mov_b32_e32 v4, v37
	v_mad_u64_u32 v[38:39], s[14:15], v38, s48, v[4:5]
	v_cndmask_b32_e32 v13, v36, v32, vcc
	v_cndmask_b32_e32 v4, v38, v34, vcc
	v_cndmask_b32_e32 v31, v39, v36, vcc
	v_cndmask_b32_e64 v29, v4, v13, s[10:11]
	v_cndmask_b32_e64 v4, v31, v4, s[10:11]
	v_cndmask_b32_e32 v31, v34, v30, vcc
	v_cndmask_b32_e64 v13, v13, v31, s[10:11]
	v_sub_u32_e32 v33, 32, v15
	v_cmp_eq_u32_e64 s[14:15], 0, v15
	v_cndmask_b32_e32 v15, v32, v28, vcc
	v_cndmask_b32_e64 v4, v4, v29, s[12:13]
	v_cndmask_b32_e64 v29, v29, v13, s[12:13]
	v_cndmask_b32_e64 v28, v31, v15, s[10:11]
	v_alignbit_b32 v34, v4, v29, v33
	v_cndmask_b32_e64 v13, v13, v28, s[12:13]
	v_cndmask_b32_e64 v4, v34, v4, s[14:15]
	v_alignbit_b32 v31, v29, v13, v33
	v_cndmask_b32_e32 v12, v30, v12, vcc
	v_cndmask_b32_e64 v29, v31, v29, s[14:15]
	v_bfe_u32 v34, v4, 29, 1
	v_cndmask_b32_e64 v12, v15, v12, s[10:11]
	v_alignbit_b32 v31, v4, v29, 30
	v_sub_u32_e32 v35, 0, v34
	v_cndmask_b32_e64 v12, v28, v12, s[12:13]
	v_xor_b32_e32 v31, v31, v35
	v_alignbit_b32 v15, v13, v12, v33
	v_cndmask_b32_e64 v13, v15, v13, s[14:15]
	v_ffbh_u32_e32 v28, v31
	v_alignbit_b32 v15, v29, v13, 30
	v_min_u32_e32 v28, 32, v28
	v_alignbit_b32 v12, v13, v12, 30
	v_xor_b32_e32 v15, v15, v35
	v_sub_u32_e32 v29, 31, v28
	v_xor_b32_e32 v12, v12, v35
	v_alignbit_b32 v30, v31, v15, v29
	v_alignbit_b32 v12, v15, v12, v29
	v_alignbit_b32 v13, v30, v12, 9
	v_ffbh_u32_e32 v15, v13
	v_min_u32_e32 v15, 32, v15
	v_lshrrev_b32_e32 v32, 29, v4
	v_not_b32_e32 v29, v15
	v_alignbit_b32 v12, v13, v12, v29
	v_lshlrev_b32_e32 v13, 31, v32
	v_or_b32_e32 v29, 0x33000000, v13
	v_add_lshl_u32 v15, v15, v28, 23
	v_lshrrev_b32_e32 v12, 9, v12
	v_sub_u32_e32 v15, v29, v15
	v_or_b32_e32 v13, 0.5, v13
	v_lshlrev_b32_e32 v28, 23, v28
	v_or_b32_e32 v12, v15, v12
	v_lshrrev_b32_e32 v15, 9, v30
	v_sub_u32_e32 v13, v13, v28
	v_or_b32_e32 v13, v15, v13
	v_mul_f32_e32 v15, 0x3fc90fda, v13
	v_fma_f32 v28, v13, s49, -v15
	v_fmac_f32_e32 v28, 0x33a22168, v13
	v_fmac_f32_e32 v28, 0x3fc90fda, v12
	v_lshrrev_b32_e32 v4, 30, v4
	v_add_f32_e32 v12, v15, v28
	v_add_u32_e32 v4, v34, v4
